# v15 plus small per-XCD-slot start stagger also on phases 2 (retention/SWA) and 7 (cross-attention)
# baseline (speedup 1.0000x reference)
; __global__ void __launch_bounds__(512, 2) fwd_mega(Params p) {
;     ...
;     if (IN(2)) {
;         swa_build_bias(p, L, tid);
.LBB0_516:
	s_cmp_lt_i32 s66, 3
	s_cselect_b64 s[0:1], -1, 0
	s_and_b64 s[0:1], s[0:1], s[2:3]
	v_writelane_b32 v254, s0, 24
	s_andn2_b64 vcc, exec, s[0:1]
	s_nop 0
	v_writelane_b32 v254, s1, 25
	s_cbranch_vccnz .LBB0_633
	s_and_b32 s98, s64, 7
	s_cmp_eq_u32 s98, 0
	s_cbranch_scc1 .Lstg2_done

; #define LAS __attribute__((address_space(3)))
; DI void swa_build_bias(const Params& p, lptr L, int tid) {
;     LAS float* bl = (LAS float*)(L + L_BIAS);
;     for (int i = tid; i < 16 * 256; i += 512) { const int hq = i >> 8, idx = i & 255; const int rel = idx - 191; const int n = rel < 0 ? -rel : rel;
;         int large = 2 + (31 - __builtin_clz((unsigned)(n * n) | 1u)); large = large < 15 ? large : 15;
;         const int bucket = (rel > 0 ? 16 : 0) + (n < 8 ? n : large);
;         bl[i] = p.relb[bucket * 16 + hq]; }
; }
.Lstg2_done:
	s_movk_i32 s2, 0xbf
	v_subrev_co_u32_sdwa v0, vcc, s2, v153 dst_sel:DWORD dst_unused:UNUSED_PAD src0_sel:DWORD src1_sel:BYTE_0
	s_mov_b64 s[0:1], vcc
	v_sub_co_u32_sdwa v1, vcc, s2, v153 dst_sel:DWORD dst_unused:UNUSED_PAD src0_sel:DWORD src1_sel:BYTE_0
	v_cndmask_b32_e64 v0, v0, v1, s[0:1]
	v_mul_i32_i24_e32 v1, v0, v0
	v_or_b32_e32 v1, 1, v1
	v_ffbh_u32_e32 v1, v1
	v_sub_u32_e32 v1, 33, v1
	v_cndmask_b32_e64 v2, 0, 16, vcc
	v_min_u32_e32 v1, 15, v1
	v_cmp_gt_u32_e32 vcc, 8, v0
	v_readlane_b32 s0, v254, 7
	v_readlane_b32 s1, v254, 8
	v_cndmask_b32_e32 v0, v1, v0, vcc
	v_or_b32_e32 v0, v0, v2
	v_lshlrev_b32_e32 v2, 4, v0
	v_lshrrev_b32_e32 v0, 8, v153
	v_or_b32_e32 v0, v0, v2
	v_mov_b32_e32 v1, 0
	v_add_u32_e32 v167, 0x200, v153
	v_lshl_add_u64 v[4:5], v[0:1], 2, s[0:1]
	v_lshrrev_b32_e32 v0, 8, v167
	v_or_b32_e32 v0, v0, v2
	v_or_b32_e32 v7, 0x400, v153
	v_lshl_add_u64 v[8:9], v[0:1], 2, s[0:1]
	v_lshrrev_b32_e32 v0, 8, v7
	v_or_b32_e32 v0, v0, v2
	v_add_u32_e32 v6, 0x600, v153
	v_lshl_add_u64 v[10:11], v[0:1], 2, s[0:1]
	v_lshrrev_b32_e32 v0, 8, v6
	v_or_b32_e32 v0, v0, v2
	v_or_b32_e32 v20, 0x800, v153
	v_lshl_add_u64 v[12:13], v[0:1], 2, s[0:1]
	v_lshrrev_b32_e32 v0, 8, v20
	v_or_b32_e32 v0, v0, v2
	v_lshl_add_u64 v[14:15], v[0:1], 2, s[0:1]
	v_add_u32_e32 v0, 0xa00, v153
	v_lshrrev_b32_e32 v0, 8, v0
	v_or_b32_e32 v0, v0, v2
	v_or_b32_e32 v21, 0xc00, v153
	v_lshl_add_u64 v[16:17], v[0:1], 2, s[0:1]
	v_lshrrev_b32_e32 v0, 8, v21
	v_or_b32_e32 v0, v0, v2
	v_lshl_add_u64 v[18:19], v[0:1], 2, s[0:1]
	global_load_dword v0, v[4:5], off
	global_load_dword v22, v[8:9], off
	global_load_dword v23, v[10:11], off
	global_load_dword v24, v[12:13], off
	global_load_dword v25, v[14:15], off
	global_load_dword v26, v[16:17], off
	global_load_dword v27, v[18:19], off
	s_add_i32 s0, 0, 0x1e800
	s_movk_i32 s1, 0xe00
	v_lshl_add_u32 v3, v153, 2, s0
	v_cmp_gt_u32_e32 vcc, s1, v21
	v_readlane_b32 s2, v254, 9
	v_readlane_b32 s3, v254, 10
	v_readlane_b32 s4, v254, 11
	v_readlane_b32 s5, v254, 12
	v_readlane_b32 s6, v254, 13
	v_readlane_b32 s7, v254, 14
	v_readlane_b32 s8, v254, 15
	v_readlane_b32 s9, v254, 16
	v_readlane_b32 s10, v254, 17
	v_readlane_b32 s11, v254, 18
	v_readlane_b32 s12, v254, 19
	v_readlane_b32 s13, v254, 20
	v_readlane_b32 s14, v254, 21
	v_readlane_b32 s15, v254, 22
	v_lshl_add_u32 v4, v7, 2, s0
	v_lshl_add_u32 v5, v20, 2, s0
	v_lshl_add_u32 v7, v21, 2, s0
	s_waitcnt vmcnt(0)
	ds_write2st64_b32 v3, v0, v22 offset1:8
	ds_write_b32 v4, v23
	ds_write_b32 v5, v25
	ds_write2st64_b32 v3, v24, v26 offset0:24 offset1:40
	ds_write_b32 v7, v27
	s_and_saveexec_b64 s[0:1], vcc
	s_cbranch_execz .LBB0_519
	v_add_u32_e32 v0, 0xe00, v153
	v_lshrrev_b32_e32 v0, 8, v0
	v_readlane_b32 s4, v254, 7
	v_add_u32_e32 v0, v0, v2
	v_readlane_b32 s5, v254, 8
	v_readlane_b32 s6, v254, 9
	v_readlane_b32 s7, v254, 10
	v_lshl_add_u64 v[0:1], v[0:1], 2, s[4:5]
	global_load_dword v0, v[0:1], off
	v_readlane_b32 s8, v254, 11
	v_readlane_b32 s9, v254, 12
	v_readlane_b32 s10, v254, 13
	v_readlane_b32 s11, v254, 14
	v_readlane_b32 s12, v254, 15
	v_readlane_b32 s13, v254, 16
	v_readlane_b32 s14, v254, 17
	v_readlane_b32 s15, v254, 18
	v_readlane_b32 s16, v254, 19
	v_readlane_b32 s17, v254, 20
	v_readlane_b32 s18, v254, 21
	v_readlane_b32 s19, v254, 22
	s_waitcnt vmcnt(0)
	ds_write_b32 v3, v0 offset:14336

; __global__ void __launch_bounds__(512, 2) fwd_mega(Params p) {
;     ...
;     if (IN(7)) {
;     ...
;         cross_phase(p, L, tid, lane, wave, true);
;     ...
;         cross_phase(p, L, tid, lane, wave, true, 1);
;     ...
;         cross_phase(p, L, tid, lane, wave, true, 2);
;     ...
;         cross_phase(p, L, tid, lane, wave); }
.LBB0_1051:
	s_cmp_lt_i32 s66, 8
	s_cselect_b64 s[2:3], -1, 0
	s_and_b64 s[0:1], s[2:3], s[0:1]
	s_andn2_b64 vcc, exec, s[0:1]
	s_cbranch_vccnz .LBB0_1094
	s_and_b32 s98, s64, 7
	s_cmp_eq_u32 s98, 0
	s_cbranch_scc1 .Lstg7_done

; DI int cross_unit_of(int item, int c, int G) { if (G != 256) return item * G + c; if (item < 8) return ((8 * item + (c & 7)) << 5) + (c >> 3); return (item == 8 && c < 64) ? 2048 + c : -1; }
;     ...
;     const int G = gridDim.x, NU = 2048 + 64, cbk = blockIdx.x; const int l15 = lane & 15, g4 = lane >> 4;
;     int item = 0, unit = cross_unit_of(0, cbk, G); if (unit < 0 || unit >= NU) return;
;     u32x4 pre[4];
;     CrU u = cross_decode(p, unit);
.Lstg7_done:
	s_cmpk_lg_i32 s65, 0x100
	s_cselect_b64 s[6:7], -1, 0
	s_lshl_b32 s2, s64, 5
	s_and_b32 s4, s2, 0xe0
	s_ashr_i32 s2, s64, 3
	s_add_i32 s4, s4, s2
	s_cmpk_eq_i32 s65, 0x100
	s_cselect_b32 s9, s4, s64
	s_cmpk_gt_u32 s9, 0x83f
	s_cbranch_scc1 .LBB0_1094
	s_cmpk_gt_u32 s9, 0x7ff
	s_cbranch_scc1 .LBB0_1056
	s_lshr_b32 s8, s9, 7
	s_lshl_b32 s3, s9, 7
	s_lshl_b32 s2, s8, 12
	s_and_b32 s3, s3, 0xf80
	s_lshr_b32 s5, s9, 5
	s_or_b32 s41, s2, s3
	s_cbranch_execz .LBB0_1057
	s_movk_i32 s33, 0x80
	s_mov_b64 s[2:3], 0x3df90000
	s_branch .LBB0_1058
